# v11 plus odd WGs enter the GLU gate GEMM 12us late
# baseline (speedup 1.0000x reference)
;     __device__ void init(int M, int N, int G_, int c_, unsigned long long mask_ = 0ull) { nM = M / BM; nN = mask_ ? __builtin_popcountll(mask_) : N / BM; nwg = nM * nN; G = G_; c = c_; mask = mask_; }
; #define LAUNDER() do { tid = threadIdx.x; asm volatile("" : "+v"(tid)); lane = tid & 63; wid = __builtin_amdgcn_readfirstlane(tid >> 6); bx = blockIdx.x; asm volatile("" : "+s"(bx)); \
;         vcu = (G % 8 == 0) ? (bx % 8) * (G / 8) + bx / 8 : bx; gw = vcu * 8 + wid; ws = P.ws; asm volatile("" : "+s"(ws)); Q.ws = ws; XB = (bf16_t*)(ws + WS_XB); } while (0)
; __global__ void __launch_bounds__(512, 2) trunk_fwd(Params P) {
;     ...
;         LAUNDER();
;     ...
;         if (PH(8)) {   pg8::Gemm g{(const bf16_t*)(ws + WS_YG8), (const bf16_t*)(ws + WS_WGLU), T, AW, AW / 2}; pg8::StaticOrder S; S.init(T, AW, G, bx);
;             Epi<EPI_GLU> E{}; E.O = (bf16_t*)(ws + WS_ZS); E.ldc = AW; E.X1 = (const bf16_t*)(ws + WS_YG); E.sc_all = 1.0f / 64.0f;
;             pg8::gemm_phase<Epi<EPI_GLU>, pg8::StaticOrder, true>(lds, g, S, E); }
.LBB0_496:
	s_or_b64 exec, exec, s[2:3]
	s_waitcnt lgkmcnt(0)
	v_mov_b32_e32 v0, v160
	v_readlane_b32 s18, v252, 50
	s_mov_b64 s[16:17], s[44:45]
	v_mov_b32_e32 v8, v160
	s_barrier
	s_bitcmp1_b32 s18, 0
	s_cbranch_scc0 .Lstagger_p5_done
	s_sleep 127
	s_sleep 127
	s_sleep 127
.Lstagger_p5_done:
	s_cmpk_gt_i32 s18, 0x1ff
	v_readfirstlane_b32 s1, v8
	v_readlane_b32 s26, v254, 46
	v_readlane_b32 s31, v254, 47
	s_mov_b32 s64, s56
	s_mov_b64 s[66:67], s[92:93]
	s_mov_b64 s[68:69], s[34:35]
	s_cbranch_scc1 .LBB0_520
	s_ashr_i32 s19, s18, 31
	s_lshr_b32 s0, s19, 29
	s_add_i32 s4, s18, s0
	s_and_b32 s0, s4, -8
	s_sub_i32 s0, s18, s0
	s_cmp_gt_i32 s0, -1
	s_mov_b64 s[2:3], -1
	s_cbranch_scc0 .LBB0_499
	s_lshl_b32 s6, s0, 6
	s_mov_b64 s[2:3], 0
